# unit-loop vmcnt(0) before each K-loop hoisted to loop preheader (6 GEMM instances), on top of v1
# baseline (speedup 1.0000x reference)
.LBB0_614:
	v_readlane_b32 s44, v252, 22
	v_readlane_b32 s56, v252, 34
	v_readlane_b32 s57, v252, 35
	s_lshl_b64 s[6:7], s[6:7], 2
	v_readlane_b32 s58, v252, 36
	v_readlane_b32 s59, v252, 37
	s_mov_b64 s[24:25], s[56:57]
	s_add_u32 s14, s24, s6
	s_addc_u32 s15, s25, s7
	s_add_u32 s16, s10, 0x2d00000
	s_addc_u32 s17, s11, 0
	s_add_u32 s41, s10, 0x14400000
	s_addc_u32 s42, s11, 0
	s_add_u32 s43, s10, 0x3800000
	v_and_b32_e32 v16, 48, v15
	v_lshlrev_b32_e32 v17, 6, v15
	s_movk_i32 s7, 0x3c0
	v_lshlrev_b32_e32 v15, 2, v15
	v_readlane_b32 s45, v252, 23
	v_readlane_b32 s46, v252, 24
	v_readlane_b32 s47, v252, 25
	s_addc_u32 s44, s11, 0
	s_and_b32 s10, s18, 3
	s_lshl_b32 s6, s9, 13
	v_and_or_b32 v16, v17, s7, v16
	v_and_b32_e32 v15, 32, v15
	s_add_i32 m0, s37, 0x18000
	v_lshl_add_u64 v[8:9], v[8:9], 0, s[94:95]
	s_lshl_b32 s45, s9, 6
	v_bitop3_b32 v17, v16, s6, v15 bitop3:0xde
	s_lshl_b32 s6, s10, 12
	s_waitcnt vmcnt(2)
	s_barrier
	global_load_lds_dwordx4 v[8:9], off
	v_lshl_add_u64 v[6:7], v[6:7], 0, s[94:95]
	s_add_i32 m0, s37, 0x1a000
	s_add_i32 s46, s37, 0x8000
	s_add_i32 s47, s37, 0xa000
	v_bitop3_b32 v167, v16, s6, v15 bitop3:0xde
	global_load_lds_dwordx4 v[6:7], off
	v_lshl_add_u64 v[2:3], v[2:3], 0, s[94:95]
	s_mov_b32 m0, s46
	s_add_u32 s6, s4, 0x40080
	global_load_lds_dwordx4 v[2:3], off
	v_lshl_add_u64 v[2:3], v[4:5], 0, s[94:95]
	s_mov_b32 m0, s47
	s_addc_u32 s7, s5, 0
	global_load_lds_dwordx4 v[2:3], off
	s_add_i32 m0, s37, 0x1c000
	v_lshl_add_u64 v[2:3], s[6:7], 0, v[158:159]
	global_load_lds_dwordx4 v[2:3], off
	v_lshl_add_u64 v[2:3], s[6:7], 0, v[154:155]
	s_add_i32 m0, s37, 0x1e000
	v_readlane_b32 s48, v252, 26
	global_load_lds_dwordx4 v[2:3], off
	v_lshlrev_b32_e32 v2, 14, v13
	v_and_b32_e32 v2, 0xffff8000, v2
	v_lshl_add_u32 v2, v12, 11, v2
	v_and_b32_e32 v3, 1, v13
	v_lshl_or_b32 v2, v3, 6, v2
	v_lshl_add_u32 v162, v14, 1, v2
	v_lshlrev_b32_e32 v2, 14, v0
	s_cmpk_lt_u32 s8, 0x100
	v_and_b32_e32 v2, 0xffff8000, v2
	s_waitcnt vmcnt(6)
	s_cselect_b64 s[18:19], -1, 0
	s_lshl_b32 s48, s10, 6
	v_lshl_add_u32 v2, v10, 11, v2
	v_and_b32_e32 v0, 1, v0
	v_readlane_b32 s49, v252, 27
	v_readlane_b32 s50, v252, 28
	s_cmp_eq_u32 s10, 0
	v_lshl_or_b32 v0, v0, 6, v2
	v_readlane_b32 s6, v253, 29
	s_mov_b32 s49, 0
	s_cselect_b64 s[20:21], -1, 0
	v_mov_b32_e32 v163, v1
	v_lshl_add_u32 v164, v11, 1, v0
	v_mov_b32_e32 v165, v1
	v_add_u32_e32 v169, 0, v17
	v_readlane_b32 s10, v253, 13
	s_mov_b32 s50, s6
	v_readlane_b32 s11, v252, 55
	v_readlane_b32 s51, v252, 29
	v_readlane_b32 s52, v252, 30
	v_readlane_b32 s53, v252, 31
	v_readlane_b32 s54, v252, 32
	v_readlane_b32 s55, v252, 33
	s_mov_b64 s[26:27], s[58:59]
	s_barrier
	v_readlane_b32 s7, v253, 30
	s_waitcnt vmcnt(0)
	s_branch .LBB0_617

.LBB0_619:
	s_ashr_i32 s25, s24, 31
	s_lshl_b64 s[8:9], s[24:25], 19
	s_add_u32 s26, s34, s8
	s_addc_u32 s27, s35, s9
	s_and_b64 s[8:9], s[6:7], exec
	s_cselect_b32 s11, s27, s3
	s_cselect_b32 s25, s26, s2
	s_ashr_i32 s23, s22, 31
	s_lshl_b64 s[8:9], s[22:23], 19
	s_add_u32 s28, s30, s8
	s_addc_u32 s29, s31, s9
	s_and_b64 s[8:9], s[6:7], exec
	s_cselect_b32 s23, s29, s5
	s_cselect_b32 s51, s28, s4
	s_add_u32 s2, s2, 0x40080
	s_addc_u32 s3, s3, 0
	s_add_u32 s52, s4, 0x100
	v_mov_b32_e32 v66, 0
	s_addc_u32 s53, s5, 0
	s_mov_b32 s54, -2
	v_mov_b32_e32 v67, v66
	v_mov_b32_e32 v68, v66
	v_mov_b32_e32 v69, v66
	v_mov_b32_e32 v70, v66
	v_mov_b32_e32 v71, v66
	v_mov_b32_e32 v72, v66
	v_mov_b32_e32 v73, v66
	v_mov_b32_e32 v74, v66
	v_mov_b32_e32 v75, v66
	v_mov_b32_e32 v76, v66
	v_mov_b32_e32 v77, v66
	v_mov_b32_e32 v78, v66
	v_mov_b32_e32 v79, v66
	v_mov_b32_e32 v80, v66
	v_mov_b32_e32 v81, v66
	v_mov_b32_e32 v82, v66
	v_mov_b32_e32 v83, v66
	v_mov_b32_e32 v84, v66
	v_mov_b32_e32 v85, v66
	v_mov_b32_e32 v86, v66
	v_mov_b32_e32 v87, v66
	v_mov_b32_e32 v88, v66
	v_mov_b32_e32 v89, v66
	v_mov_b32_e32 v90, v66
	v_mov_b32_e32 v91, v66
	v_mov_b32_e32 v92, v66
	v_mov_b32_e32 v93, v66
	v_mov_b32_e32 v94, v66
	v_mov_b32_e32 v95, v66
	v_mov_b32_e32 v96, v66
	v_mov_b32_e32 v97, v66
	v_mov_b32_e32 v2, v66
	v_mov_b32_e32 v3, v66
	v_mov_b32_e32 v4, v66
	v_mov_b32_e32 v5, v66
	v_mov_b32_e32 v6, v66
	v_mov_b32_e32 v7, v66
	v_mov_b32_e32 v8, v66
	v_mov_b32_e32 v9, v66
	v_mov_b32_e32 v10, v66
	v_mov_b32_e32 v11, v66
	v_mov_b32_e32 v12, v66
	v_mov_b32_e32 v13, v66
	v_mov_b32_e32 v14, v66
	v_mov_b32_e32 v15, v66
	v_mov_b32_e32 v16, v66
	v_mov_b32_e32 v17, v66
	v_mov_b32_e32 v18, v66
	v_mov_b32_e32 v19, v66
	v_mov_b32_e32 v20, v66
	v_mov_b32_e32 v21, v66
	v_mov_b32_e32 v22, v66
	v_mov_b32_e32 v23, v66
	v_mov_b32_e32 v24, v66
	v_mov_b32_e32 v25, v66
	v_mov_b32_e32 v26, v66
	v_mov_b32_e32 v27, v66
	v_mov_b32_e32 v28, v66
	v_mov_b32_e32 v29, v66
	v_mov_b32_e32 v30, v66
	v_mov_b32_e32 v31, v66
	v_mov_b32_e32 v32, v66
	v_mov_b32_e32 v33, v66
	v_mov_b32_e32 v98, v66
	v_mov_b32_e32 v99, v66
	v_mov_b32_e32 v100, v66
	v_mov_b32_e32 v101, v66
	v_mov_b32_e32 v102, v66
	v_mov_b32_e32 v103, v66
	v_mov_b32_e32 v104, v66
	v_mov_b32_e32 v105, v66
	v_mov_b32_e32 v122, v66
	v_mov_b32_e32 v123, v66
	v_mov_b32_e32 v124, v66
	v_mov_b32_e32 v125, v66
	v_mov_b32_e32 v126, v66
	v_mov_b32_e32 v127, v66
	v_mov_b32_e32 v128, v66
	v_mov_b32_e32 v129, v66
	v_mov_b32_e32 v130, v66
	v_mov_b32_e32 v131, v66
	v_mov_b32_e32 v132, v66
	v_mov_b32_e32 v133, v66
	v_mov_b32_e32 v134, v66
	v_mov_b32_e32 v135, v66
	v_mov_b32_e32 v136, v66
	v_mov_b32_e32 v137, v66
	v_mov_b32_e32 v138, v66
	v_mov_b32_e32 v139, v66
	v_mov_b32_e32 v140, v66
	v_mov_b32_e32 v141, v66
	v_mov_b32_e32 v142, v66
	v_mov_b32_e32 v143, v66
	v_mov_b32_e32 v144, v66
	v_mov_b32_e32 v145, v66
	v_mov_b32_e32 v34, v66
	v_mov_b32_e32 v35, v66
	v_mov_b32_e32 v36, v66
	v_mov_b32_e32 v37, v66
	v_mov_b32_e32 v38, v66
	v_mov_b32_e32 v39, v66
	v_mov_b32_e32 v40, v66
	v_mov_b32_e32 v41, v66
	v_mov_b32_e32 v42, v66
	v_mov_b32_e32 v43, v66
	v_mov_b32_e32 v44, v66
	v_mov_b32_e32 v45, v66
	v_mov_b32_e32 v46, v66
	v_mov_b32_e32 v47, v66
	v_mov_b32_e32 v48, v66
	v_mov_b32_e32 v49, v66
	v_mov_b32_e32 v50, v66
	v_mov_b32_e32 v51, v66
	v_mov_b32_e32 v52, v66
	v_mov_b32_e32 v53, v66
	v_mov_b32_e32 v54, v66
	v_mov_b32_e32 v55, v66
	v_mov_b32_e32 v56, v66
	v_mov_b32_e32 v57, v66
	v_mov_b32_e32 v58, v66
	v_mov_b32_e32 v59, v66
	v_mov_b32_e32 v60, v66
	v_mov_b32_e32 v61, v66
	v_mov_b32_e32 v62, v66
	v_mov_b32_e32 v63, v66
	v_mov_b32_e32 v64, v66
	v_mov_b32_e32 v65, v66

.LBB0_998:
	s_add_u32 s4, s7, 0x4000000
	s_addc_u32 s5, s10, 0
	s_and_b32 s11, s9, 3
	v_and_b32_e32 v17, 48, v16
	v_lshlrev_b32_e32 v18, 6, v16
	s_movk_i32 s9, 0x3c0
	v_lshlrev_b32_e32 v16, 2, v16
	s_lshl_b32 s35, s8, 6
	s_lshl_b32 s8, s8, 13
	v_and_or_b32 v17, v18, s9, v17
	v_and_b32_e32 v16, 32, v16
	s_add_i32 m0, s29, 0x18000
	v_lshl_add_u64 v[8:9], v[8:9], 0, s[94:95]
	v_bitop3_b32 v18, v17, s8, v16 bitop3:0xde
	s_lshl_b32 s36, s11, 5
	s_lshl_b32 s8, s11, 12
	s_waitcnt vmcnt(2)
	s_barrier
	global_load_lds_dwordx4 v[8:9], off
	v_lshl_add_u64 v[6:7], v[6:7], 0, s[94:95]
	s_add_i32 m0, s29, 0x1a000
	s_add_i32 s37, s29, 0x8000
	s_add_i32 s38, s29, 0xa000
	v_bitop3_b32 v166, v17, s8, v16 bitop3:0xde
	global_load_lds_dwordx4 v[6:7], off
	v_lshl_add_u64 v[2:3], v[2:3], 0, s[94:95]
	s_mov_b32 m0, s37
	s_add_u32 s8, s20, 0x40080
	global_load_lds_dwordx4 v[2:3], off
	v_lshl_add_u64 v[2:3], v[4:5], 0, s[94:95]
	s_mov_b32 m0, s38
	s_addc_u32 s9, s21, 0
	global_load_lds_dwordx4 v[2:3], off
	s_add_i32 m0, s29, 0x1c000
	v_lshl_add_u64 v[2:3], s[8:9], 0, v[0:1]
	global_load_lds_dwordx4 v[2:3], off
	v_lshl_add_u64 v[2:3], s[8:9], 0, v[130:131]
	s_add_i32 m0, s29, 0x1e000
	s_cmpk_lt_u32 s6, 0x100
	global_load_lds_dwordx4 v[2:3], off
	v_lshlrev_b32_e32 v2, 14, v13
	v_and_b32_e32 v2, 0xffff8000, v2
	v_lshl_add_u32 v2, v14, 11, v2
	v_and_b32_e32 v3, 1, v13
	s_cselect_b64 s[8:9], -1, 0
	s_lshl_b32 s6, s11, 2
	v_lshl_or_b32 v2, v3, 6, v2
	s_add_u32 s6, s7, s6
	v_lshl_add_u32 v132, v15, 1, v2
	v_lshlrev_b32_e32 v2, 14, v10
	s_addc_u32 s7, s10, 0
	v_and_b32_e32 v2, 0xffff8000, v2
	s_waitcnt vmcnt(6)
	s_add_u32 s39, s6, 0x2d00000
	v_lshl_add_u32 v2, v11, 11, v2
	v_and_b32_e32 v3, 1, v10
	s_addc_u32 s40, s7, 0
	v_lshl_or_b32 v2, v3, 6, v2
	v_readlane_b32 s6, v253, 53
	v_mov_b32_e32 v133, v1
	v_lshl_add_u32 v134, v12, 1, v2
	v_mov_b32_e32 v135, v1
	s_mov_b32 s41, 0
	v_add_u32_e32 v167, 0, v18
	v_readlane_b32 s42, v253, 57
	s_mov_b32 s43, s6
	v_readlane_b32 s53, v252, 55
	s_barrier
	v_readlane_b32 s7, v253, 54
	s_waitcnt vmcnt(0)
	s_branch .LBB0_1001

.LBB0_1007:
	s_ashr_i32 s13, s12, 31
	s_lshl_b64 s[14:15], s[12:13], 19
	s_add_u32 s14, s26, s14
	s_addc_u32 s15, s27, s15
	s_and_b64 s[16:17], s[6:7], exec
	s_cselect_b32 s13, s15, s19
	s_cselect_b32 s44, s14, s18
	s_ashr_i32 s11, s10, 31
	s_lshl_b64 s[16:17], s[10:11], 19
	s_add_u32 s16, s24, s16
	s_addc_u32 s17, s25, s17
	s_and_b64 s[22:23], s[6:7], exec
	s_cselect_b32 s11, s17, s21
	s_cselect_b32 s45, s16, s20
	s_add_u32 s18, s18, 0x40080
	s_addc_u32 s19, s19, 0
	s_add_u32 s46, s20, 0x100
	v_mov_b32_e32 v2, 0
	s_addc_u32 s47, s21, 0
	s_mov_b32 s48, -2
	v_mov_b32_e32 v3, v2
	v_mov_b32_e32 v4, v2
	v_mov_b32_e32 v5, v2
	v_mov_b32_e32 v6, v2
	v_mov_b32_e32 v7, v2
	v_mov_b32_e32 v8, v2
	v_mov_b32_e32 v9, v2
	v_mov_b32_e32 v14, v2
	v_mov_b32_e32 v15, v2
	v_mov_b32_e32 v16, v2
	v_mov_b32_e32 v17, v2
	v_mov_b32_e32 v22, v2
	v_mov_b32_e32 v23, v2
	v_mov_b32_e32 v24, v2
	v_mov_b32_e32 v25, v2
	v_mov_b32_e32 v30, v2
	v_mov_b32_e32 v31, v2
	v_mov_b32_e32 v32, v2
	v_mov_b32_e32 v33, v2
	v_mov_b32_e32 v38, v2
	v_mov_b32_e32 v39, v2
	v_mov_b32_e32 v40, v2
	v_mov_b32_e32 v41, v2
	v_mov_b32_e32 v46, v2
	v_mov_b32_e32 v47, v2
	v_mov_b32_e32 v48, v2
	v_mov_b32_e32 v49, v2
	v_mov_b32_e32 v54, v2
	v_mov_b32_e32 v55, v2
	v_mov_b32_e32 v56, v2
	v_mov_b32_e32 v57, v2
	v_mov_b32_e32 v10, v2
	v_mov_b32_e32 v11, v2
	v_mov_b32_e32 v12, v2
	v_mov_b32_e32 v13, v2
	v_mov_b32_e32 v18, v2
	v_mov_b32_e32 v19, v2
	v_mov_b32_e32 v20, v2
	v_mov_b32_e32 v21, v2
	v_mov_b32_e32 v26, v2
	v_mov_b32_e32 v27, v2
	v_mov_b32_e32 v28, v2
	v_mov_b32_e32 v29, v2
	v_mov_b32_e32 v34, v2
	v_mov_b32_e32 v35, v2
	v_mov_b32_e32 v36, v2
	v_mov_b32_e32 v37, v2
	v_mov_b32_e32 v42, v2
	v_mov_b32_e32 v43, v2
	v_mov_b32_e32 v44, v2
	v_mov_b32_e32 v45, v2
	v_mov_b32_e32 v50, v2
	v_mov_b32_e32 v51, v2
	v_mov_b32_e32 v52, v2
	v_mov_b32_e32 v53, v2
	v_mov_b32_e32 v58, v2
	v_mov_b32_e32 v59, v2
	v_mov_b32_e32 v60, v2
	v_mov_b32_e32 v61, v2
	v_mov_b32_e32 v62, v2
	v_mov_b32_e32 v63, v2
	v_mov_b32_e32 v64, v2
	v_mov_b32_e32 v65, v2
	v_mov_b32_e32 v66, v2
	v_mov_b32_e32 v67, v2
	v_mov_b32_e32 v68, v2
	v_mov_b32_e32 v69, v2
	v_mov_b32_e32 v70, v2
	v_mov_b32_e32 v71, v2
	v_mov_b32_e32 v72, v2
	v_mov_b32_e32 v73, v2
	v_mov_b32_e32 v78, v2
	v_mov_b32_e32 v79, v2
	v_mov_b32_e32 v80, v2
	v_mov_b32_e32 v81, v2
	v_mov_b32_e32 v86, v2
	v_mov_b32_e32 v87, v2
	v_mov_b32_e32 v88, v2
	v_mov_b32_e32 v89, v2
	v_mov_b32_e32 v94, v2
	v_mov_b32_e32 v95, v2
	v_mov_b32_e32 v96, v2
	v_mov_b32_e32 v97, v2
	v_mov_b32_e32 v102, v2
	v_mov_b32_e32 v103, v2
	v_mov_b32_e32 v104, v2
	v_mov_b32_e32 v105, v2
	v_mov_b32_e32 v110, v2
	v_mov_b32_e32 v111, v2
	v_mov_b32_e32 v112, v2
	v_mov_b32_e32 v113, v2
	v_mov_b32_e32 v118, v2
	v_mov_b32_e32 v119, v2
	v_mov_b32_e32 v120, v2
	v_mov_b32_e32 v121, v2
	v_mov_b32_e32 v74, v2
	v_mov_b32_e32 v75, v2
	v_mov_b32_e32 v76, v2
	v_mov_b32_e32 v77, v2
	v_mov_b32_e32 v82, v2
	v_mov_b32_e32 v83, v2
	v_mov_b32_e32 v84, v2
	v_mov_b32_e32 v85, v2
	v_mov_b32_e32 v90, v2
	v_mov_b32_e32 v91, v2
	v_mov_b32_e32 v92, v2
	v_mov_b32_e32 v93, v2
	v_mov_b32_e32 v98, v2
	v_mov_b32_e32 v99, v2
	v_mov_b32_e32 v100, v2
	v_mov_b32_e32 v101, v2
	v_mov_b32_e32 v106, v2
	v_mov_b32_e32 v107, v2
	v_mov_b32_e32 v108, v2
	v_mov_b32_e32 v109, v2
	v_mov_b32_e32 v114, v2
	v_mov_b32_e32 v115, v2
	v_mov_b32_e32 v116, v2
	v_mov_b32_e32 v117, v2
	v_mov_b32_e32 v122, v2
	v_mov_b32_e32 v123, v2
	v_mov_b32_e32 v124, v2
	v_mov_b32_e32 v125, v2
	v_mov_b32_e32 v126, v2
	v_mov_b32_e32 v127, v2
	v_mov_b32_e32 v128, v2
	v_mov_b32_e32 v129, v2

.LBB0_1076:
	s_add_u32 s6, s8, 0x2d00000
	s_addc_u32 s7, s9, 0
	s_add_u32 s8, s8, 0x14400000
	s_addc_u32 s9, s9, 0
	s_lshl_b32 s11, s11, 5
	v_and_b32_e32 v17, 48, v16
	v_lshlrev_b32_e32 v18, 6, v16
	s_movk_i32 s13, 0x3c0
	v_lshlrev_b32_e32 v16, 2, v16
	s_and_b32 s43, s11, 0x60
	s_add_i32 m0, s38, 0x18000
	v_lshl_add_u64 v[8:9], v[8:9], 0, s[94:95]
	s_lshl_b32 s42, s12, 6
	s_lshl_b32 s12, s12, 13
	v_and_or_b32 v17, v18, s13, v17
	v_and_b32_e32 v16, 32, v16
	s_lshl_b32 s11, s43, 7
	s_waitcnt vmcnt(2)
	s_barrier
	global_load_lds_dwordx4 v[8:9], off
	v_lshl_add_u64 v[6:7], v[6:7], 0, s[94:95]
	s_add_i32 m0, s38, 0x1a000
	s_add_i32 s44, s38, 0x8000
	s_add_i32 s45, s38, 0xa000
	v_bitop3_b32 v18, v17, s12, v16 bitop3:0xde
	global_load_lds_dwordx4 v[6:7], off
	v_lshl_add_u64 v[2:3], v[2:3], 0, s[94:95]
	s_mov_b32 m0, s44
	s_add_u32 s12, s24, 0x40080
	global_load_lds_dwordx4 v[2:3], off
	v_lshl_add_u64 v[2:3], v[4:5], 0, s[94:95]
	s_mov_b32 m0, s45
	s_addc_u32 s13, s25, 0
	global_load_lds_dwordx4 v[2:3], off
	s_add_i32 m0, s38, 0x1c000
	v_lshl_add_u64 v[2:3], s[12:13], 0, v[0:1]
	global_load_lds_dwordx4 v[2:3], off
	v_lshl_add_u64 v[2:3], s[12:13], 0, v[130:131]
	s_add_i32 m0, s38, 0x1e000
	v_readlane_b32 s12, v253, 39
	global_load_lds_dwordx4 v[2:3], off
	v_lshlrev_b32_e32 v2, 14, v14
	v_and_b32_e32 v2, 0xffff8000, v2
	v_lshl_add_u32 v2, v13, 11, v2
	v_and_b32_e32 v3, 1, v14
	v_lshl_or_b32 v2, v3, 6, v2
	v_lshl_add_u32 v136, v15, 1, v2
	v_lshlrev_b32_e32 v2, 14, v10
	v_and_b32_e32 v2, 0xffff8000, v2
	s_waitcnt vmcnt(6)
	v_lshl_add_u32 v2, v11, 11, v2
	v_and_b32_e32 v3, 1, v10
	v_readlane_b32 s13, v253, 40
	s_cmpk_lt_u32 s10, 0x100
	v_lshl_or_b32 v2, v3, 6, v2
	s_mov_b32 s48, s12
	v_readlane_b32 s12, v253, 35
	v_bitop3_b32 v141, s11, v17, v16 bitop3:0xf6
	s_cselect_b64 s[10:11], -1, 0
	v_mov_b32_e32 v137, v1
	v_lshl_add_u32 v138, v12, 1, v2
	v_mov_b32_e32 v139, v1
	s_mov_b32 s46, 0
	v_add_u32_e32 v143, 0, v18
	s_mov_b32 s47, s12
	v_readlane_b32 s26, v252, 55
	s_barrier
	v_readlane_b32 s13, v253, 36
	s_waitcnt vmcnt(0)
	s_branch .LBB0_1079

.LBB0_1082:
	s_ashr_i32 s15, s14, 31
	s_lshl_b64 s[18:19], s[14:15], 19
	s_add_u32 s18, s29, s18
	s_addc_u32 s19, s30, s19
	s_and_b64 s[20:21], s[16:17], exec
	s_cselect_b32 s15, s19, s23
	s_cselect_b32 s49, s18, s22
	s_ashr_i32 s13, s12, 31
	s_lshl_b64 s[20:21], s[12:13], 19
	s_add_u32 s20, s31, s20
	s_addc_u32 s21, s36, s21
	s_and_b64 s[26:27], s[16:17], exec
	s_cselect_b32 s13, s21, s25
	s_cselect_b32 s50, s20, s24
	s_add_u32 s22, s22, 0x40080
	s_addc_u32 s23, s23, 0
	s_add_u32 s51, s24, 0x100
	v_mov_b32_e32 v2, 0
	s_addc_u32 s52, s25, 0
	s_mov_b32 s53, -2
	v_mov_b32_e32 v3, v2
	v_mov_b32_e32 v4, v2
	v_mov_b32_e32 v5, v2
	v_mov_b32_e32 v10, v2
	v_mov_b32_e32 v11, v2
	v_mov_b32_e32 v12, v2
	v_mov_b32_e32 v13, v2
	v_mov_b32_e32 v18, v2
	v_mov_b32_e32 v19, v2
	v_mov_b32_e32 v20, v2
	v_mov_b32_e32 v21, v2
	v_mov_b32_e32 v26, v2
	v_mov_b32_e32 v27, v2
	v_mov_b32_e32 v28, v2
	v_mov_b32_e32 v29, v2
	v_mov_b32_e32 v34, v2
	v_mov_b32_e32 v35, v2
	v_mov_b32_e32 v36, v2
	v_mov_b32_e32 v37, v2
	v_mov_b32_e32 v42, v2
	v_mov_b32_e32 v43, v2
	v_mov_b32_e32 v44, v2
	v_mov_b32_e32 v45, v2
	v_mov_b32_e32 v50, v2
	v_mov_b32_e32 v51, v2
	v_mov_b32_e32 v52, v2
	v_mov_b32_e32 v53, v2
	v_mov_b32_e32 v58, v2
	v_mov_b32_e32 v59, v2
	v_mov_b32_e32 v60, v2
	v_mov_b32_e32 v61, v2
	v_mov_b32_e32 v6, v2
	v_mov_b32_e32 v7, v2
	v_mov_b32_e32 v8, v2
	v_mov_b32_e32 v9, v2
	v_mov_b32_e32 v14, v2
	v_mov_b32_e32 v15, v2
	v_mov_b32_e32 v16, v2
	v_mov_b32_e32 v17, v2
	v_mov_b32_e32 v22, v2
	v_mov_b32_e32 v23, v2
	v_mov_b32_e32 v24, v2
	v_mov_b32_e32 v25, v2
	v_mov_b32_e32 v30, v2
	v_mov_b32_e32 v31, v2
	v_mov_b32_e32 v32, v2
	v_mov_b32_e32 v33, v2
	v_mov_b32_e32 v38, v2
	v_mov_b32_e32 v39, v2
	v_mov_b32_e32 v40, v2
	v_mov_b32_e32 v41, v2
	v_mov_b32_e32 v46, v2
	v_mov_b32_e32 v47, v2
	v_mov_b32_e32 v48, v2
	v_mov_b32_e32 v49, v2
	v_mov_b32_e32 v54, v2
	v_mov_b32_e32 v55, v2
	v_mov_b32_e32 v56, v2
	v_mov_b32_e32 v57, v2
	v_mov_b32_e32 v62, v2
	v_mov_b32_e32 v63, v2
	v_mov_b32_e32 v64, v2
	v_mov_b32_e32 v65, v2
	v_mov_b32_e32 v66, v2
	v_mov_b32_e32 v67, v2
	v_mov_b32_e32 v68, v2
	v_mov_b32_e32 v69, v2
	v_mov_b32_e32 v74, v2
	v_mov_b32_e32 v75, v2
	v_mov_b32_e32 v76, v2
	v_mov_b32_e32 v77, v2
	v_mov_b32_e32 v82, v2
	v_mov_b32_e32 v83, v2
	v_mov_b32_e32 v84, v2
	v_mov_b32_e32 v85, v2
	v_mov_b32_e32 v90, v2
	v_mov_b32_e32 v91, v2
	v_mov_b32_e32 v92, v2
	v_mov_b32_e32 v93, v2
	v_mov_b32_e32 v98, v2
	v_mov_b32_e32 v99, v2
	v_mov_b32_e32 v100, v2
	v_mov_b32_e32 v101, v2
	v_mov_b32_e32 v106, v2
	v_mov_b32_e32 v107, v2
	v_mov_b32_e32 v108, v2
	v_mov_b32_e32 v109, v2
	v_mov_b32_e32 v114, v2
	v_mov_b32_e32 v115, v2
	v_mov_b32_e32 v116, v2
	v_mov_b32_e32 v117, v2
	v_mov_b32_e32 v122, v2
	v_mov_b32_e32 v123, v2
	v_mov_b32_e32 v124, v2
	v_mov_b32_e32 v125, v2
	v_mov_b32_e32 v70, v2
	v_mov_b32_e32 v71, v2
	v_mov_b32_e32 v72, v2
	v_mov_b32_e32 v73, v2
	v_mov_b32_e32 v78, v2
	v_mov_b32_e32 v79, v2
	v_mov_b32_e32 v80, v2
	v_mov_b32_e32 v81, v2
	v_mov_b32_e32 v86, v2
	v_mov_b32_e32 v87, v2
	v_mov_b32_e32 v88, v2
	v_mov_b32_e32 v89, v2
	v_mov_b32_e32 v94, v2
	v_mov_b32_e32 v95, v2
	v_mov_b32_e32 v96, v2
	v_mov_b32_e32 v97, v2
	v_mov_b32_e32 v102, v2
	v_mov_b32_e32 v103, v2
	v_mov_b32_e32 v104, v2
	v_mov_b32_e32 v105, v2
	v_mov_b32_e32 v110, v2
	v_mov_b32_e32 v111, v2
	v_mov_b32_e32 v112, v2
	v_mov_b32_e32 v113, v2
	v_mov_b32_e32 v118, v2
	v_mov_b32_e32 v119, v2
	v_mov_b32_e32 v120, v2
	v_mov_b32_e32 v121, v2
	v_mov_b32_e32 v126, v2
	v_mov_b32_e32 v127, v2
	v_mov_b32_e32 v128, v2
	v_mov_b32_e32 v129, v2

.LBB0_1227:
	s_add_u32 s4, s6, 0x2d00000
	s_addc_u32 s5, s7, 0
	s_add_u32 s6, s6, 0x14400000
	s_addc_u32 s7, s7, 0
	s_lshl_b32 s9, s9, 5
	v_and_b32_e32 v17, 48, v16
	v_lshlrev_b32_e32 v18, 6, v16
	s_movk_i32 s13, 0x3c0
	v_lshlrev_b32_e32 v16, 2, v16
	s_and_b32 s44, s9, 0x60
	s_add_i32 m0, s25, 0x18000
	v_lshl_add_u64 v[8:9], v[8:9], 0, s[94:95]
	s_lshl_b32 s43, s12, 6
	s_lshl_b32 s12, s12, 13
	v_and_or_b32 v17, v18, s13, v17
	v_and_b32_e32 v16, 32, v16
	s_lshl_b32 s9, s44, 7
	s_waitcnt vmcnt(2)
	s_barrier
	global_load_lds_dwordx4 v[8:9], off
	v_lshl_add_u64 v[6:7], v[6:7], 0, s[94:95]
	s_add_i32 m0, s25, 0x1a000
	s_add_i32 s45, s25, 0x8000
	s_add_i32 s46, s25, 0xa000
	v_bitop3_b32 v18, v17, s12, v16 bitop3:0xde
	global_load_lds_dwordx4 v[6:7], off
	v_lshl_add_u64 v[2:3], v[2:3], 0, s[94:95]
	s_mov_b32 m0, s45
	s_add_u32 s12, s28, 0x40080
	global_load_lds_dwordx4 v[2:3], off
	v_lshl_add_u64 v[2:3], v[4:5], 0, s[94:95]
	s_mov_b32 m0, s46
	s_addc_u32 s13, s29, 0
	global_load_lds_dwordx4 v[2:3], off
	s_add_i32 m0, s25, 0x1c000
	v_lshl_add_u64 v[2:3], s[12:13], 0, v[0:1]
	global_load_lds_dwordx4 v[2:3], off
	v_lshl_add_u64 v[2:3], s[12:13], 0, v[130:131]
	s_add_i32 m0, s25, 0x1e000
	s_cmpk_lt_u32 s8, 0x100
	global_load_lds_dwordx4 v[2:3], off
	v_lshlrev_b32_e32 v2, 14, v14
	v_and_b32_e32 v2, 0xffff8000, v2
	v_lshl_add_u32 v2, v13, 11, v2
	v_and_b32_e32 v3, 1, v14
	v_lshl_or_b32 v2, v3, 6, v2
	v_lshl_add_u32 v136, v15, 1, v2
	v_lshlrev_b32_e32 v2, 14, v10
	v_and_b32_e32 v2, 0xffff8000, v2
	s_waitcnt vmcnt(6)
	v_lshl_add_u32 v2, v11, 11, v2
	v_and_b32_e32 v3, 1, v10
	v_lshl_or_b32 v2, v3, 6, v2
	v_bitop3_b32 v141, s9, v17, v16 bitop3:0xf6
	s_cselect_b64 s[8:9], -1, 0
	v_mov_b32_e32 v137, v1
	v_lshl_add_u32 v138, v12, 1, v2
	v_mov_b32_e32 v139, v1
	s_mov_b32 s47, 0
	v_add_u32_e32 v143, 0, v18
	v_readlane_b32 s55, v252, 55
	s_barrier
	s_waitcnt vmcnt(0)
	s_branch .LBB0_1230

.LBB0_1237:
	s_mov_b32 s14, s15
	s_ashr_i32 s15, s15, 31
	s_lshl_b64 s[18:19], s[14:15], 19
	s_add_u32 s18, s36, s18
	s_addc_u32 s19, s37, s19
	s_mov_b32 s12, s20
	s_and_b64 s[20:21], s[16:17], exec
	s_cselect_b32 s15, s19, s27
	s_cselect_b32 s23, s18, s26
	s_ashr_i32 s13, s12, 31
	s_lshl_b64 s[20:21], s[12:13], 19
	s_add_u32 s20, s34, s20
	s_addc_u32 s21, s38, s21
	s_and_b64 s[30:31], s[16:17], exec
	s_cselect_b32 s13, s21, s29
	s_cselect_b32 s48, s20, s28
	s_add_u32 s26, s26, 0x40080
	s_addc_u32 s27, s27, 0
	s_add_u32 s49, s28, 0x100
	v_mov_b32_e32 v2, 0
	s_addc_u32 s50, s29, 0
	s_mov_b32 s51, -2
	v_mov_b32_e32 v3, v2
	v_mov_b32_e32 v4, v2
	v_mov_b32_e32 v5, v2
	v_mov_b32_e32 v10, v2
	v_mov_b32_e32 v11, v2
	v_mov_b32_e32 v12, v2
	v_mov_b32_e32 v13, v2
	v_mov_b32_e32 v18, v2
	v_mov_b32_e32 v19, v2
	v_mov_b32_e32 v20, v2
	v_mov_b32_e32 v21, v2
	v_mov_b32_e32 v26, v2
	v_mov_b32_e32 v27, v2
	v_mov_b32_e32 v28, v2
	v_mov_b32_e32 v29, v2
	v_mov_b32_e32 v34, v2
	v_mov_b32_e32 v35, v2
	v_mov_b32_e32 v36, v2
	v_mov_b32_e32 v37, v2
	v_mov_b32_e32 v42, v2
	v_mov_b32_e32 v43, v2
	v_mov_b32_e32 v44, v2
	v_mov_b32_e32 v45, v2
	v_mov_b32_e32 v50, v2
	v_mov_b32_e32 v51, v2
	v_mov_b32_e32 v52, v2
	v_mov_b32_e32 v53, v2
	v_mov_b32_e32 v58, v2
	v_mov_b32_e32 v59, v2
	v_mov_b32_e32 v60, v2
	v_mov_b32_e32 v61, v2
	v_mov_b32_e32 v6, v2
	v_mov_b32_e32 v7, v2
	v_mov_b32_e32 v8, v2
	v_mov_b32_e32 v9, v2
	v_mov_b32_e32 v14, v2
	v_mov_b32_e32 v15, v2
	v_mov_b32_e32 v16, v2
	v_mov_b32_e32 v17, v2
	v_mov_b32_e32 v22, v2
	v_mov_b32_e32 v23, v2
	v_mov_b32_e32 v24, v2
	v_mov_b32_e32 v25, v2
	v_mov_b32_e32 v30, v2
	v_mov_b32_e32 v31, v2
	v_mov_b32_e32 v32, v2
	v_mov_b32_e32 v33, v2
	v_mov_b32_e32 v38, v2
	v_mov_b32_e32 v39, v2
	v_mov_b32_e32 v40, v2
	v_mov_b32_e32 v41, v2
	v_mov_b32_e32 v46, v2
	v_mov_b32_e32 v47, v2
	v_mov_b32_e32 v48, v2
	v_mov_b32_e32 v49, v2
	v_mov_b32_e32 v54, v2
	v_mov_b32_e32 v55, v2
	v_mov_b32_e32 v56, v2
	v_mov_b32_e32 v57, v2
	v_mov_b32_e32 v62, v2
	v_mov_b32_e32 v63, v2
	v_mov_b32_e32 v64, v2
	v_mov_b32_e32 v65, v2
	v_mov_b32_e32 v66, v2
	v_mov_b32_e32 v67, v2
	v_mov_b32_e32 v68, v2
	v_mov_b32_e32 v69, v2
	v_mov_b32_e32 v74, v2
	v_mov_b32_e32 v75, v2
	v_mov_b32_e32 v76, v2
	v_mov_b32_e32 v77, v2
	v_mov_b32_e32 v82, v2
	v_mov_b32_e32 v83, v2
	v_mov_b32_e32 v84, v2
	v_mov_b32_e32 v85, v2
	v_mov_b32_e32 v90, v2
	v_mov_b32_e32 v91, v2
	v_mov_b32_e32 v92, v2
	v_mov_b32_e32 v93, v2
	v_mov_b32_e32 v98, v2
	v_mov_b32_e32 v99, v2
	v_mov_b32_e32 v100, v2
	v_mov_b32_e32 v101, v2
	v_mov_b32_e32 v106, v2
	v_mov_b32_e32 v107, v2
	v_mov_b32_e32 v108, v2
	v_mov_b32_e32 v109, v2
	v_mov_b32_e32 v114, v2
	v_mov_b32_e32 v115, v2
	v_mov_b32_e32 v116, v2
	v_mov_b32_e32 v117, v2
	v_mov_b32_e32 v122, v2
	v_mov_b32_e32 v123, v2
	v_mov_b32_e32 v124, v2
	v_mov_b32_e32 v125, v2
	v_mov_b32_e32 v70, v2
	v_mov_b32_e32 v71, v2
	v_mov_b32_e32 v72, v2
	v_mov_b32_e32 v73, v2
	v_mov_b32_e32 v78, v2
	v_mov_b32_e32 v79, v2
	v_mov_b32_e32 v80, v2
	v_mov_b32_e32 v81, v2
	v_mov_b32_e32 v86, v2
	v_mov_b32_e32 v87, v2
	v_mov_b32_e32 v88, v2
	v_mov_b32_e32 v89, v2
	v_mov_b32_e32 v94, v2
	v_mov_b32_e32 v95, v2
	v_mov_b32_e32 v96, v2
	v_mov_b32_e32 v97, v2
	v_mov_b32_e32 v102, v2
	v_mov_b32_e32 v103, v2
	v_mov_b32_e32 v104, v2
	v_mov_b32_e32 v105, v2
	v_mov_b32_e32 v110, v2
	v_mov_b32_e32 v111, v2
	v_mov_b32_e32 v112, v2
	v_mov_b32_e32 v113, v2
	v_mov_b32_e32 v118, v2
	v_mov_b32_e32 v119, v2
	v_mov_b32_e32 v120, v2
	v_mov_b32_e32 v121, v2
	v_mov_b32_e32 v126, v2
	v_mov_b32_e32 v127, v2
	v_mov_b32_e32 v128, v2
	v_mov_b32_e32 v129, v2

.LBB0_1302:
	s_lshl_b32 s11, s11, 5
	v_readlane_b32 s44, v252, 22
	v_and_b32_e32 v19, 48, v18
	v_lshlrev_b32_e32 v20, 6, v18
	s_movk_i32 s13, 0x3c0
	v_lshlrev_b32_e32 v18, 2, v18
	s_and_b32 s40, s11, 0x60
	v_readlane_b32 s52, v252, 30
	v_readlane_b32 s53, v252, 31
	v_readlane_b32 s54, v252, 32
	v_readlane_b32 s55, v252, 33
	v_readlane_b32 s56, v252, 34
	v_readlane_b32 s57, v252, 35
	s_lshl_b32 s39, s12, 6
	s_lshl_b32 s12, s12, 13
	v_and_or_b32 v19, v20, s13, v19
	v_and_b32_e32 v18, 32, v18
	s_lshl_b32 s11, s40, 7
	s_lshl_b64 s[8:9], s[8:9], 2
	v_readlane_b32 s58, v252, 36
	v_readlane_b32 s59, v252, 37
	s_mov_b64 s[52:53], s[56:57]
	v_bitop3_b32 v20, v19, s12, v18 bitop3:0xde
	s_add_u32 s12, s52, s8
	s_addc_u32 s13, s53, s9
	s_add_i32 m0, s31, 0x18000
	v_lshl_add_u64 v[8:9], v[8:9], 0, s[94:95]
	s_waitcnt vmcnt(2)
	s_barrier
	global_load_lds_dwordx4 v[8:9], off
	v_lshl_add_u64 v[6:7], v[6:7], 0, s[94:95]
	s_add_i32 m0, s31, 0x1a000
	s_add_i32 s41, s31, 0x8000
	s_add_i32 s42, s31, 0xa000
	global_load_lds_dwordx4 v[6:7], off
	v_lshl_add_u64 v[2:3], v[2:3], 0, s[94:95]
	s_mov_b32 m0, s41
	s_add_u32 s8, s20, 0xb0080
	global_load_lds_dwordx4 v[2:3], off
	v_lshl_add_u64 v[2:3], v[4:5], 0, s[94:95]
	s_mov_b32 m0, s42
	s_addc_u32 s9, s21, 0
	global_load_lds_dwordx4 v[2:3], off
	s_add_i32 m0, s31, 0x1c000
	v_lshl_add_u64 v[2:3], s[8:9], 0, v[0:1]
	global_load_lds_dwordx4 v[2:3], off
	v_lshl_add_u64 v[2:3], s[8:9], 0, v[130:131]
	s_add_i32 m0, s31, 0x1e000
	s_cmpk_lt_u32 s10, 0x100
	global_load_lds_dwordx4 v[2:3], off
	s_movk_i32 s10, 0xb00
	v_bitop3_b32 v144, s11, v19, v18 bitop3:0xf6
	v_lshrrev_b32_e32 v3, 1, v15
	v_mul_lo_u32 v2, v14, s10
	s_mov_b32 s11, 0xb000
	v_mad_u64_u32 v[2:3], s[8:9], v3, s11, v[2:3]
	v_or_b32_e32 v2, v2, v16
	v_add_lshl_u32 v2, v2, v17, 1
	v_mov_b32_e32 v3, v1
	s_mov_b64 s[16:17], 0xb0080
	v_lshl_add_u64 v[132:133], v[2:3], 0, s[16:17]
	v_lshrrev_b32_e32 v3, 1, v10
	v_mul_lo_u32 v2, v11, s10
	v_mad_u64_u32 v[2:3], s[8:9], v3, s11, v[2:3]
	s_waitcnt vmcnt(6)
	v_or_b32_e32 v2, v2, v12
	v_readlane_b32 s46, v252, 24
	v_readlane_b32 s47, v252, 25
	v_add_lshl_u32 v2, v2, v13, 1
	v_mov_b32_e32 v3, v1
	v_readlane_b32 s8, v253, 53
	v_readlane_b32 s45, v252, 23
	s_cselect_b64 s[14:15], -1, 0
	v_lshl_add_u64 v[134:135], v[2:3], 0, s[16:17]
	s_mov_b32 s43, 0
	v_add_u32_e32 v145, 0, v20
	v_readlane_b32 s47, v253, 57
	s_mov_b32 s46, s8
	v_readlane_b32 s53, v252, 55
	v_readlane_b32 s48, v252, 26
	v_readlane_b32 s49, v252, 27
	v_readlane_b32 s50, v252, 28
	v_readlane_b32 s51, v252, 29
	s_mov_b64 s[54:55], s[58:59]
	s_barrier
	v_readlane_b32 s9, v253, 54
	s_waitcnt vmcnt(0)
	s_branch .LBB0_1305

.LBB0_1315:
	s_add_u32 s48, s20, 0x100
	v_mov_b32_e32 v2, 0
	s_addc_u32 s49, s21, 0
	s_mov_b32 s50, -2
	v_mov_b32_e32 v3, v2
	v_mov_b32_e32 v4, v2
	v_mov_b32_e32 v5, v2
	v_mov_b32_e32 v6, v2
	v_mov_b32_e32 v7, v2
	v_mov_b32_e32 v8, v2
	v_mov_b32_e32 v9, v2
	v_mov_b32_e32 v14, v2
	v_mov_b32_e32 v15, v2
	v_mov_b32_e32 v16, v2
	v_mov_b32_e32 v17, v2
	v_mov_b32_e32 v22, v2
	v_mov_b32_e32 v23, v2
	v_mov_b32_e32 v24, v2
	v_mov_b32_e32 v25, v2
	v_mov_b32_e32 v30, v2
	v_mov_b32_e32 v31, v2
	v_mov_b32_e32 v32, v2
	v_mov_b32_e32 v33, v2
	v_mov_b32_e32 v38, v2
	v_mov_b32_e32 v39, v2
	v_mov_b32_e32 v40, v2
	v_mov_b32_e32 v41, v2
	v_mov_b32_e32 v46, v2
	v_mov_b32_e32 v47, v2
	v_mov_b32_e32 v48, v2
	v_mov_b32_e32 v49, v2
	v_mov_b32_e32 v54, v2
	v_mov_b32_e32 v55, v2
	v_mov_b32_e32 v56, v2
	v_mov_b32_e32 v57, v2
	v_mov_b32_e32 v10, v2
	v_mov_b32_e32 v11, v2
	v_mov_b32_e32 v12, v2
	v_mov_b32_e32 v13, v2
	v_mov_b32_e32 v18, v2
	v_mov_b32_e32 v19, v2
	v_mov_b32_e32 v20, v2
	v_mov_b32_e32 v21, v2
	v_mov_b32_e32 v26, v2
	v_mov_b32_e32 v27, v2
	v_mov_b32_e32 v28, v2
	v_mov_b32_e32 v29, v2
	v_mov_b32_e32 v34, v2
	v_mov_b32_e32 v35, v2
	v_mov_b32_e32 v36, v2
	v_mov_b32_e32 v37, v2
	v_mov_b32_e32 v42, v2
	v_mov_b32_e32 v43, v2
	v_mov_b32_e32 v44, v2
	v_mov_b32_e32 v45, v2
	v_mov_b32_e32 v50, v2
	v_mov_b32_e32 v51, v2
	v_mov_b32_e32 v52, v2
	v_mov_b32_e32 v53, v2
	v_mov_b32_e32 v58, v2
	v_mov_b32_e32 v59, v2
	v_mov_b32_e32 v60, v2
	v_mov_b32_e32 v61, v2
	v_mov_b32_e32 v62, v2
	v_mov_b32_e32 v63, v2
	v_mov_b32_e32 v64, v2
	v_mov_b32_e32 v65, v2
	v_mov_b32_e32 v66, v2
	v_mov_b32_e32 v67, v2
	v_mov_b32_e32 v68, v2
	v_mov_b32_e32 v69, v2
	v_mov_b32_e32 v70, v2
	v_mov_b32_e32 v71, v2
	v_mov_b32_e32 v72, v2
	v_mov_b32_e32 v73, v2
	v_mov_b32_e32 v78, v2
	v_mov_b32_e32 v79, v2
	v_mov_b32_e32 v80, v2
	v_mov_b32_e32 v81, v2
	v_mov_b32_e32 v86, v2
	v_mov_b32_e32 v87, v2
	v_mov_b32_e32 v88, v2
	v_mov_b32_e32 v89, v2
	v_mov_b32_e32 v94, v2
	v_mov_b32_e32 v95, v2
	v_mov_b32_e32 v96, v2
	v_mov_b32_e32 v97, v2
	v_mov_b32_e32 v102, v2
	v_mov_b32_e32 v103, v2
	v_mov_b32_e32 v104, v2
	v_mov_b32_e32 v105, v2
	v_mov_b32_e32 v110, v2
	v_mov_b32_e32 v111, v2
	v_mov_b32_e32 v112, v2
	v_mov_b32_e32 v113, v2
	v_mov_b32_e32 v118, v2
	v_mov_b32_e32 v119, v2
	v_mov_b32_e32 v120, v2
	v_mov_b32_e32 v121, v2
	v_mov_b32_e32 v74, v2
	v_mov_b32_e32 v75, v2
	v_mov_b32_e32 v76, v2
	v_mov_b32_e32 v77, v2
	v_mov_b32_e32 v82, v2
	v_mov_b32_e32 v83, v2
	v_mov_b32_e32 v84, v2
	v_mov_b32_e32 v85, v2
	v_mov_b32_e32 v90, v2
	v_mov_b32_e32 v91, v2
	v_mov_b32_e32 v92, v2
	v_mov_b32_e32 v93, v2
	v_mov_b32_e32 v98, v2
	v_mov_b32_e32 v99, v2
	v_mov_b32_e32 v100, v2
	v_mov_b32_e32 v101, v2
	v_mov_b32_e32 v106, v2
	v_mov_b32_e32 v107, v2
	v_mov_b32_e32 v108, v2
	v_mov_b32_e32 v109, v2
	v_mov_b32_e32 v114, v2
	v_mov_b32_e32 v115, v2
	v_mov_b32_e32 v116, v2
	v_mov_b32_e32 v117, v2
	v_mov_b32_e32 v122, v2
	v_mov_b32_e32 v123, v2
	v_mov_b32_e32 v124, v2
	v_mov_b32_e32 v125, v2
	v_mov_b32_e32 v126, v2
	v_mov_b32_e32 v127, v2
	v_mov_b32_e32 v128, v2
	v_mov_b32_e32 v129, v2

.LBB0_1328:
	s_and_b32 s12, s8, 3
	v_and_b32_e32 v19, 48, v18
	v_lshlrev_b32_e32 v20, 6, v18
	s_movk_i32 s8, 0x3c0
	v_lshlrev_b32_e32 v18, 2, v18
	s_lshl_b32 s31, s7, 6
	s_lshl_b32 s7, s7, 13
	v_and_or_b32 v19, v20, s8, v19
	v_and_b32_e32 v18, 32, v18
	s_add_i32 m0, s23, 0x18000
	v_lshl_add_u64 v[8:9], v[8:9], 0, s[94:95]
	v_bitop3_b32 v20, v19, s7, v18 bitop3:0xde
	s_lshl_b32 s36, s12, 5
	s_lshl_b32 s7, s12, 12
	s_waitcnt vmcnt(2)
	s_barrier
	global_load_lds_dwordx4 v[8:9], off
	v_lshl_add_u64 v[6:7], v[6:7], 0, s[94:95]
	s_add_i32 m0, s23, 0x1a000
	s_add_i32 s37, s23, 0x8000
	s_add_i32 s38, s23, 0xa000
	global_load_lds_dwordx4 v[6:7], off
	v_lshl_add_u64 v[2:3], v[2:3], 0, s[94:95]
	s_mov_b32 m0, s37
	s_add_u32 s8, s16, 0xb0080
	global_load_lds_dwordx4 v[2:3], off
	v_lshl_add_u64 v[2:3], v[4:5], 0, s[94:95]
	s_mov_b32 m0, s38
	s_addc_u32 s9, s17, 0
	global_load_lds_dwordx4 v[2:3], off
	s_add_i32 m0, s23, 0x1c000
	v_lshl_add_u64 v[2:3], s[8:9], 0, v[0:1]
	global_load_lds_dwordx4 v[2:3], off
	v_lshl_add_u64 v[2:3], s[8:9], 0, v[130:131]
	s_add_i32 m0, s23, 0x1e000
	s_cmpk_lt_u32 s6, 0x100
	global_load_lds_dwordx4 v[2:3], off
	s_cselect_b64 s[10:11], -1, 0
	s_lshl_b32 s6, s12, 2
	s_add_u32 s6, s34, s6
	v_bitop3_b32 v166, v19, s7, v18 bitop3:0xde
	s_addc_u32 s7, s35, 0
	s_movk_i32 s8, 0xb00
	s_add_u32 s34, s6, 0x2d00000
	v_lshrrev_b32_e32 v3, 1, v15
	v_mul_lo_u32 v2, v14, s8
	s_mov_b32 s9, 0xb000
	s_addc_u32 s35, s7, 0
	v_mad_u64_u32 v[2:3], s[6:7], v3, s9, v[2:3]
	v_or_b32_e32 v2, v2, v16
	v_add_lshl_u32 v2, v2, v17, 1
	v_mov_b32_e32 v3, v1
	s_mov_b64 s[12:13], 0xb0080
	v_lshl_add_u64 v[132:133], v[2:3], 0, s[12:13]
	v_lshrrev_b32_e32 v3, 1, v10
	v_mul_lo_u32 v2, v11, s8
	v_mad_u64_u32 v[2:3], s[6:7], v3, s9, v[2:3]
	s_waitcnt vmcnt(6)
	v_or_b32_e32 v2, v2, v12
	v_add_lshl_u32 v2, v2, v13, 1
	v_mov_b32_e32 v3, v1
	v_readlane_b32 s6, v253, 53
	v_lshl_add_u64 v[134:135], v[2:3], 0, s[12:13]
	s_mov_b32 s39, 0
	v_add_u32_e32 v167, 0, v20
	v_readlane_b32 s40, v253, 57
	s_mov_b32 s43, s6
	v_readlane_b32 s49, v252, 55
	s_barrier
	v_readlane_b32 s7, v253, 54
	s_waitcnt vmcnt(0)
	s_branch .LBB0_1331

.LBB0_1341:
	s_add_u32 s44, s16, 0x100
	v_mov_b32_e32 v2, 0
	s_addc_u32 s45, s17, 0
	s_mov_b32 s46, -2
	v_mov_b32_e32 v3, v2
	v_mov_b32_e32 v4, v2
	v_mov_b32_e32 v5, v2
	v_mov_b32_e32 v6, v2
	v_mov_b32_e32 v7, v2
	v_mov_b32_e32 v8, v2
	v_mov_b32_e32 v9, v2
	v_mov_b32_e32 v14, v2
	v_mov_b32_e32 v15, v2
	v_mov_b32_e32 v16, v2
	v_mov_b32_e32 v17, v2
	v_mov_b32_e32 v22, v2
	v_mov_b32_e32 v23, v2
	v_mov_b32_e32 v24, v2
	v_mov_b32_e32 v25, v2
	v_mov_b32_e32 v30, v2
	v_mov_b32_e32 v31, v2
	v_mov_b32_e32 v32, v2
	v_mov_b32_e32 v33, v2
	v_mov_b32_e32 v38, v2
	v_mov_b32_e32 v39, v2
	v_mov_b32_e32 v40, v2
	v_mov_b32_e32 v41, v2
	v_mov_b32_e32 v46, v2
	v_mov_b32_e32 v47, v2
	v_mov_b32_e32 v48, v2
	v_mov_b32_e32 v49, v2
	v_mov_b32_e32 v54, v2
	v_mov_b32_e32 v55, v2
	v_mov_b32_e32 v56, v2
	v_mov_b32_e32 v57, v2
	v_mov_b32_e32 v10, v2
	v_mov_b32_e32 v11, v2
	v_mov_b32_e32 v12, v2
	v_mov_b32_e32 v13, v2
	v_mov_b32_e32 v18, v2
	v_mov_b32_e32 v19, v2
	v_mov_b32_e32 v20, v2
	v_mov_b32_e32 v21, v2
	v_mov_b32_e32 v26, v2
	v_mov_b32_e32 v27, v2
	v_mov_b32_e32 v28, v2
	v_mov_b32_e32 v29, v2
	v_mov_b32_e32 v34, v2
	v_mov_b32_e32 v35, v2
	v_mov_b32_e32 v36, v2
	v_mov_b32_e32 v37, v2
	v_mov_b32_e32 v42, v2
	v_mov_b32_e32 v43, v2
	v_mov_b32_e32 v44, v2
	v_mov_b32_e32 v45, v2
	v_mov_b32_e32 v50, v2
	v_mov_b32_e32 v51, v2
	v_mov_b32_e32 v52, v2
	v_mov_b32_e32 v53, v2
	v_mov_b32_e32 v58, v2
	v_mov_b32_e32 v59, v2
	v_mov_b32_e32 v60, v2
	v_mov_b32_e32 v61, v2
	v_mov_b32_e32 v62, v2
	v_mov_b32_e32 v63, v2
	v_mov_b32_e32 v64, v2
	v_mov_b32_e32 v65, v2
	v_mov_b32_e32 v66, v2
	v_mov_b32_e32 v67, v2
	v_mov_b32_e32 v68, v2
	v_mov_b32_e32 v69, v2
	v_mov_b32_e32 v70, v2
	v_mov_b32_e32 v71, v2
	v_mov_b32_e32 v72, v2
	v_mov_b32_e32 v73, v2
	v_mov_b32_e32 v78, v2
	v_mov_b32_e32 v79, v2
	v_mov_b32_e32 v80, v2
	v_mov_b32_e32 v81, v2
	v_mov_b32_e32 v86, v2
	v_mov_b32_e32 v87, v2
	v_mov_b32_e32 v88, v2
	v_mov_b32_e32 v89, v2
	v_mov_b32_e32 v94, v2
	v_mov_b32_e32 v95, v2
	v_mov_b32_e32 v96, v2
	v_mov_b32_e32 v97, v2
	v_mov_b32_e32 v102, v2
	v_mov_b32_e32 v103, v2
	v_mov_b32_e32 v104, v2
	v_mov_b32_e32 v105, v2
	v_mov_b32_e32 v110, v2
	v_mov_b32_e32 v111, v2
	v_mov_b32_e32 v112, v2
	v_mov_b32_e32 v113, v2
	v_mov_b32_e32 v118, v2
	v_mov_b32_e32 v119, v2
	v_mov_b32_e32 v120, v2
	v_mov_b32_e32 v121, v2
	v_mov_b32_e32 v74, v2
	v_mov_b32_e32 v75, v2
	v_mov_b32_e32 v76, v2
	v_mov_b32_e32 v77, v2
	v_mov_b32_e32 v82, v2
	v_mov_b32_e32 v83, v2
	v_mov_b32_e32 v84, v2
	v_mov_b32_e32 v85, v2
	v_mov_b32_e32 v90, v2
	v_mov_b32_e32 v91, v2
	v_mov_b32_e32 v92, v2
	v_mov_b32_e32 v93, v2
	v_mov_b32_e32 v98, v2
	v_mov_b32_e32 v99, v2
	v_mov_b32_e32 v100, v2
	v_mov_b32_e32 v101, v2
	v_mov_b32_e32 v106, v2
	v_mov_b32_e32 v107, v2
	v_mov_b32_e32 v108, v2
	v_mov_b32_e32 v109, v2
	v_mov_b32_e32 v114, v2
	v_mov_b32_e32 v115, v2
	v_mov_b32_e32 v116, v2
	v_mov_b32_e32 v117, v2
	v_mov_b32_e32 v122, v2
	v_mov_b32_e32 v123, v2
	v_mov_b32_e32 v124, v2
	v_mov_b32_e32 v125, v2
	v_mov_b32_e32 v126, v2
	v_mov_b32_e32 v127, v2
	v_mov_b32_e32 v128, v2
	v_mov_b32_e32 v129, v2
